# w_up weight-copy tile: all 16 loads issued before the bf16 packing (no early vmcnt(0)); PanelRms partial loads issued together
# speedup vs baseline: 1.0012x; 1.0012x over previous
.LBB0_857:
	s_mov_b64 s[6:7], -1
	s_cmpk_gt_i32 s5, 0xaff
	v_lshlrev_b32_e32 v196, 2, v60
	v_add_u32_e32 v98, 0x400, v66
	v_lshlrev_b32_e32 v64, 1, v62
	v_add_u32_e32 v96, 0x2040, v82
	v_add_u32_e32 v97, 0x2048, v82
	v_add_u32_e32 v94, 0x4080, v82
	v_add_u32_e32 v95, 0x4088, v82
	v_add_u32_e32 v92, 0x60c0, v82
	v_add_u32_e32 v93, 0x60c8, v82
	v_add_u32_e32 v90, 0x8100, v82
	v_add_u32_e32 v91, 0x8108, v82
	v_add_u32_e32 v88, 0xa140, v82
	v_add_u32_e32 v89, 0xa148, v82
	v_add_u32_e32 v86, 0xc180, v82
	v_add_u32_e32 v87, 0xc188, v82
	v_add_u32_e32 v84, 0xe1c0, v82
	v_add_u32_e32 v85, 0xe1c8, v82
	s_cbranch_scc0 .LBB0_859
	s_and_b32 s6, s4, 0xffff
	s_mul_hi_u32 s8, s6, 0xba2e8c
	s_mul_i32 s6, s8, 0x160
	s_mul_i32 s7, s5, 0xba2f
	s_sub_i32 s6, s4, s6
	s_add_i32 s7, s7, 0xf7fffb00
	s_lshr_b32 s9, s7, 24
	s_bfe_u32 s7, s6, 0x4001b
	s_add_i32 s6, s6, s7
	s_sext_i32_i16 s6, s6
	s_ashr_i32 s26, s6, 4
	s_mov_b64 s[6:7], s[0:1]
	s_load_dwordx2 s[6:7], s[6:7], 0x90
	s_mov_b64 s[24:25], s[0:1]
	s_load_dwordx2 s[24:25], s[24:25], 0xa8
	s_mul_i32 s27, s9, 0x2c00000
	s_mul_hi_u32 s19, s9, 0x2c00000
	s_waitcnt lgkmcnt(0)
	s_add_u32 s28, s6, s27
	s_addc_u32 s7, s7, s19
	s_mul_hi_u32 s6, s9, 0x1600000
	s_mul_i32 s9, s9, 0x1600000
	s_add_u32 s19, s24, s9
	s_addc_u32 s24, s25, s6
	s_lshl_b32 s9, s26, 11
	s_add_i32 s25, s82, s2
	s_mul_i32 s8, s8, 0xffff5000
	s_sub_i32 s25, s25, s9
	s_lshl_b32 s6, s26, 8
	s_add_i32 s26, s25, s8
	s_ashr_i32 s27, s26, 31
	v_add_u32_e32 v4, s6, v63
	s_lshl_b64 s[26:27], s[26:27], 2
	s_add_u32 s26, s28, s26
	v_ashrrev_i32_e32 v5, 31, v4
	s_addc_u32 s27, s7, s27
	v_lshlrev_b64 v[0:1], 13, v[4:5]
	v_or_b32_e32 v4, 1, v4
	v_lshl_add_u64 v[6:7], s[26:27], 0, v[196:197]
	v_ashrrev_i32_e32 v5, 31, v4
	v_lshl_add_u64 v[56:57], v[6:7], 0, v[0:1]
	v_lshlrev_b64 v[4:5], 13, v[4:5]
	global_load_dwordx4 v[0:3], v[56:57], off nt
	v_lshl_add_u64 v[4:5], v[6:7], 0, v[4:5]
	global_load_dwordx4 v[4:7], v[4:5], off nt
	v_add_co_u32_e32 v8, vcc, s73, v56
	s_mov_b32 s7, 0x42000
	s_nop 0
	v_addc_co_u32_e32 v9, vcc, 0, v57, vcc
	v_add_co_u32_e32 v12, vcc, s7, v56
	s_mov_b32 s7, 0x82000
	s_nop 0
	v_addc_co_u32_e32 v13, vcc, 0, v57, vcc
	global_load_dwordx4 v[8:11], v[8:9], off nt
	global_load_dwordx4 v[12:15], v[12:13], off nt
	v_add_co_u32_e32 v16, vcc, s90, v56
	s_nop 1
	v_addc_co_u32_e32 v17, vcc, 0, v57, vcc
	v_add_co_u32_e32 v20, vcc, s7, v56
	s_mov_b32 s7, 0xc2000
	s_nop 0
	v_addc_co_u32_e32 v21, vcc, 0, v57, vcc
	global_load_dwordx4 v[16:19], v[16:17], off nt
	global_load_dwordx4 v[20:23], v[20:21], off nt
	v_add_co_u32_e32 v24, vcc, s33, v56
	s_nop 1
	v_addc_co_u32_e32 v25, vcc, 0, v57, vcc
	v_add_co_u32_e32 v28, vcc, s7, v56
	s_mov_b32 s7, 0x102000
	s_nop 0
	v_addc_co_u32_e32 v29, vcc, 0, v57, vcc
	global_load_dwordx4 v[24:27], v[24:25], off nt
	global_load_dwordx4 v[28:31], v[28:29], off nt
	v_add_co_u32_e32 v32, vcc, s52, v56
	s_nop 1
	v_addc_co_u32_e32 v33, vcc, 0, v57, vcc
	v_add_co_u32_e32 v36, vcc, s7, v56
	s_mov_b32 s7, 0x142000
	s_nop 0
	v_addc_co_u32_e32 v37, vcc, 0, v57, vcc
	global_load_dwordx4 v[32:35], v[32:33], off nt
	global_load_dwordx4 v[36:39], v[36:37], off nt
	v_add_co_u32_e32 v40, vcc, s54, v56
	s_nop 1
	v_addc_co_u32_e32 v41, vcc, 0, v57, vcc
	v_add_co_u32_e32 v44, vcc, s7, v56
	s_mov_b32 s7, 0x180000
	s_nop 0
	v_addc_co_u32_e32 v45, vcc, 0, v57, vcc
	global_load_dwordx4 v[40:43], v[40:41], off nt
	global_load_dwordx4 v[44:47], v[44:45], off nt
	v_add_co_u32_e32 v48, vcc, s7, v56
	s_mov_b32 s7, 0x182000
	s_nop 0
	v_addc_co_u32_e32 v49, vcc, 0, v57, vcc
	v_add_co_u32_e32 v52, vcc, s7, v56
	s_nop 1
	v_addc_co_u32_e32 v53, vcc, 0, v57, vcc
	global_load_dwordx4 v[48:51], v[48:49], off nt
	global_load_dwordx4 v[52:55], v[52:53], off nt
	s_mov_b32 s7, 0x1c0000
	v_add_co_u32_e32 v58, vcc, s7, v56
	s_nop 1
	v_addc_co_u32_e32 v59, vcc, 0, v57, vcc
	s_mov_b32 s7, 0x1c2000
	v_add_co_u32_e32 v100, vcc, s7, v56
	s_nop 1
	v_addc_co_u32_e32 v101, vcc, 0, v57, vcc
	global_load_dwordx4 v[56:59], v[58:59], off nt
	global_load_dwordx4 v[100:103], v[100:101], off nt
	s_waitcnt vmcnt(12)
	v_bfe_u32 v65, v0, 16, 1
	v_add3_u32 v0, v0, v65, s66
	v_bfe_u32 v65, v4, 16, 1
	v_lshrrev_b32_e32 v0, 16, v0
	v_add3_u32 v4, v4, v65, s66
	v_and_or_b32 v0, v4, s63, v0
	v_bfe_u32 v4, v1, 16, 1
	v_add3_u32 v1, v1, v4, s66
	v_bfe_u32 v4, v5, 16, 1
	v_lshrrev_b32_e32 v1, 16, v1
	v_add3_u32 v4, v5, v4, s66
	v_and_or_b32 v1, v4, s63, v1
	v_bfe_u32 v4, v2, 16, 1
	v_add3_u32 v2, v2, v4, s66
	v_bfe_u32 v4, v6, 16, 1
	v_lshrrev_b32_e32 v2, 16, v2
	v_add3_u32 v4, v6, v4, s66
	v_and_or_b32 v2, v4, s63, v2
	v_bfe_u32 v4, v3, 16, 1
	v_add3_u32 v3, v3, v4, s66
	v_bfe_u32 v4, v7, 16, 1
	v_lshrrev_b32_e32 v3, 16, v3
	v_add3_u32 v4, v7, v4, s66
	v_and_or_b32 v3, v4, s63, v3
	v_bfe_u32 v4, v8, 16, 1
	v_add3_u32 v4, v8, v4, s66
	v_bfe_u32 v5, v12, 16, 1
	v_lshrrev_b32_e32 v4, 16, v4
	v_add3_u32 v5, v12, v5, s66
	v_and_or_b32 v4, v5, s63, v4
	ds_write2_b32 v66, v0, v4 offset1:16
	v_bfe_u32 v0, v9, 16, 1
	v_add3_u32 v0, v9, v0, s66
	v_bfe_u32 v4, v13, 16, 1
	v_lshrrev_b32_e32 v0, 16, v0
	v_add3_u32 v4, v13, v4, s66
	v_and_or_b32 v0, v4, s63, v0
	ds_write2_b32 v66, v1, v0 offset0:129 offset1:145
	v_bfe_u32 v0, v10, 16, 1
	v_add3_u32 v0, v10, v0, s66
	v_bfe_u32 v1, v14, 16, 1
	v_lshrrev_b32_e32 v0, 16, v0
	v_add3_u32 v1, v14, v1, s66
	v_and_or_b32 v0, v1, s63, v0
	ds_write2_b32 v98, v2, v0 offset0:2 offset1:18
	v_bfe_u32 v0, v11, 16, 1
	v_add3_u32 v0, v11, v0, s66
	v_bfe_u32 v1, v15, 16, 1
	v_lshrrev_b32_e32 v0, 16, v0
	v_add3_u32 v1, v15, v1, s66
	v_and_or_b32 v0, v1, s63, v0
	ds_write2_b32 v98, v3, v0 offset0:131 offset1:147
	s_waitcnt vmcnt(11)
	v_bfe_u32 v0, v16, 16, 1
	v_add3_u32 v0, v16, v0, s66
	s_waitcnt vmcnt(10)
	v_bfe_u32 v1, v20, 16, 1
	v_lshrrev_b32_e32 v0, 16, v0
	v_add3_u32 v1, v20, v1, s66
	v_and_or_b32 v0, v1, s63, v0
	v_bfe_u32 v1, v17, 16, 1
	v_add3_u32 v1, v17, v1, s66
	v_bfe_u32 v2, v21, 16, 1
	v_lshrrev_b32_e32 v1, 16, v1
	v_add3_u32 v2, v21, v2, s66
	v_and_or_b32 v1, v2, s63, v1
	v_bfe_u32 v2, v18, 16, 1
	v_add3_u32 v2, v18, v2, s66
	v_bfe_u32 v3, v22, 16, 1
	v_lshrrev_b32_e32 v2, 16, v2
	v_add3_u32 v3, v22, v3, s66
	v_and_or_b32 v2, v3, s63, v2
	v_bfe_u32 v3, v19, 16, 1
	v_add3_u32 v3, v19, v3, s66
	v_bfe_u32 v4, v23, 16, 1
	v_lshrrev_b32_e32 v3, 16, v3
	v_add3_u32 v4, v23, v4, s66
	v_and_or_b32 v3, v4, s63, v3
	s_waitcnt vmcnt(9)
	v_bfe_u32 v4, v24, 16, 1
	v_add3_u32 v4, v24, v4, s66
	s_waitcnt vmcnt(8)
	v_bfe_u32 v5, v28, 16, 1
	v_lshrrev_b32_e32 v4, 16, v4
	v_add3_u32 v5, v28, v5, s66
	v_and_or_b32 v4, v5, s63, v4
	ds_write2_b32 v66, v0, v4 offset0:32 offset1:48
	v_bfe_u32 v0, v25, 16, 1
	v_add3_u32 v0, v25, v0, s66
	v_bfe_u32 v4, v29, 16, 1
	v_lshrrev_b32_e32 v0, 16, v0
	v_add3_u32 v4, v29, v4, s66
	v_and_or_b32 v0, v4, s63, v0
	ds_write2_b32 v66, v1, v0 offset0:161 offset1:177
	v_bfe_u32 v0, v26, 16, 1
	v_add3_u32 v0, v26, v0, s66
	v_bfe_u32 v1, v30, 16, 1
	v_lshrrev_b32_e32 v0, 16, v0
	v_add3_u32 v1, v30, v1, s66
	v_and_or_b32 v0, v1, s63, v0
	ds_write2_b32 v98, v2, v0 offset0:34 offset1:50
	v_bfe_u32 v0, v27, 16, 1
	v_add3_u32 v0, v27, v0, s66
	v_bfe_u32 v1, v31, 16, 1
	v_lshrrev_b32_e32 v0, 16, v0
	v_add3_u32 v1, v31, v1, s66
	v_and_or_b32 v0, v1, s63, v0
	ds_write2_b32 v98, v3, v0 offset0:163 offset1:179
	s_waitcnt vmcnt(7)
	v_bfe_u32 v0, v32, 16, 1
	v_add3_u32 v0, v32, v0, s66
	s_waitcnt vmcnt(6)
	v_bfe_u32 v1, v36, 16, 1
	v_lshrrev_b32_e32 v0, 16, v0
	v_add3_u32 v1, v36, v1, s66
	v_and_or_b32 v0, v1, s63, v0
	v_bfe_u32 v1, v33, 16, 1
	v_add3_u32 v1, v33, v1, s66
	v_bfe_u32 v2, v37, 16, 1
	v_lshrrev_b32_e32 v1, 16, v1
	v_add3_u32 v2, v37, v2, s66
	v_and_or_b32 v1, v2, s63, v1
	v_bfe_u32 v2, v34, 16, 1
	v_add3_u32 v2, v34, v2, s66
	v_bfe_u32 v3, v38, 16, 1
	v_lshrrev_b32_e32 v2, 16, v2
	v_add3_u32 v3, v38, v3, s66
	v_and_or_b32 v2, v3, s63, v2
	v_bfe_u32 v3, v35, 16, 1
	v_add3_u32 v3, v35, v3, s66
	v_bfe_u32 v4, v39, 16, 1
	v_lshrrev_b32_e32 v3, 16, v3
	v_add3_u32 v4, v39, v4, s66
	v_and_or_b32 v3, v4, s63, v3
	s_waitcnt vmcnt(5)
	v_bfe_u32 v4, v40, 16, 1
	v_add3_u32 v4, v40, v4, s66
	s_waitcnt vmcnt(4)
	v_bfe_u32 v5, v44, 16, 1
	v_lshrrev_b32_e32 v4, 16, v4
	v_add3_u32 v5, v44, v5, s66
	v_and_or_b32 v4, v5, s63, v4
	ds_write2_b32 v66, v0, v4 offset0:64 offset1:80
	v_bfe_u32 v0, v41, 16, 1
	v_add3_u32 v0, v41, v0, s66
	v_bfe_u32 v4, v45, 16, 1
	v_lshrrev_b32_e32 v0, 16, v0
	v_add3_u32 v4, v45, v4, s66
	v_and_or_b32 v0, v4, s63, v0
	ds_write2_b32 v66, v1, v0 offset0:193 offset1:209
	v_bfe_u32 v0, v42, 16, 1
	v_add3_u32 v0, v42, v0, s66
	v_bfe_u32 v1, v46, 16, 1
	v_lshrrev_b32_e32 v0, 16, v0
	v_add3_u32 v1, v46, v1, s66
	v_and_or_b32 v0, v1, s63, v0
	ds_write2_b32 v98, v2, v0 offset0:66 offset1:82
	v_bfe_u32 v0, v43, 16, 1
	v_add3_u32 v0, v43, v0, s66
	v_bfe_u32 v1, v47, 16, 1
	v_lshrrev_b32_e32 v0, 16, v0
	v_add3_u32 v1, v47, v1, s66
	v_and_or_b32 v0, v1, s63, v0
	ds_write2_b32 v98, v3, v0 offset0:195 offset1:211
	s_waitcnt vmcnt(3)
	v_bfe_u32 v0, v48, 16, 1
	v_add3_u32 v0, v48, v0, s66
	s_waitcnt vmcnt(2)
	v_bfe_u32 v1, v52, 16, 1
	v_lshrrev_b32_e32 v0, 16, v0
	v_add3_u32 v1, v52, v1, s66
	v_and_or_b32 v0, v1, s63, v0
	v_bfe_u32 v1, v49, 16, 1
	v_add3_u32 v1, v49, v1, s66
	v_bfe_u32 v2, v53, 16, 1
	v_lshrrev_b32_e32 v1, 16, v1
	v_add3_u32 v2, v53, v2, s66
	v_and_or_b32 v1, v2, s63, v1
	v_bfe_u32 v2, v50, 16, 1
	v_add3_u32 v2, v50, v2, s66
	v_bfe_u32 v3, v54, 16, 1
	v_lshrrev_b32_e32 v2, 16, v2
	v_add3_u32 v3, v54, v3, s66
	v_and_or_b32 v2, v3, s63, v2
	v_bfe_u32 v3, v51, 16, 1
	v_add3_u32 v3, v51, v3, s66
	v_bfe_u32 v4, v55, 16, 1
	v_lshrrev_b32_e32 v3, 16, v3
	v_add3_u32 v4, v55, v4, s66
	v_and_or_b32 v3, v4, s63, v3
	s_waitcnt vmcnt(1)
	v_bfe_u32 v4, v56, 16, 1
	v_add3_u32 v4, v56, v4, s66
	s_waitcnt vmcnt(0)
	v_bfe_u32 v5, v100, 16, 1
	v_lshrrev_b32_e32 v4, 16, v4
	v_add3_u32 v5, v100, v5, s66
	v_and_or_b32 v4, v5, s63, v4
	ds_write2_b32 v66, v0, v4 offset0:96 offset1:112
	v_bfe_u32 v0, v57, 16, 1
	v_add3_u32 v0, v57, v0, s66
	v_bfe_u32 v4, v101, 16, 1
	v_lshrrev_b32_e32 v0, 16, v0
	v_add3_u32 v4, v101, v4, s66
	v_and_or_b32 v0, v4, s63, v0
	ds_write2_b32 v66, v1, v0 offset0:225 offset1:241
	v_bfe_u32 v0, v58, 16, 1
	v_add3_u32 v0, v58, v0, s66
	v_bfe_u32 v1, v102, 16, 1
	v_lshrrev_b32_e32 v0, 16, v0
	v_add3_u32 v1, v102, v1, s66
	v_and_or_b32 v0, v1, s63, v0
	ds_write2_b32 v98, v2, v0 offset0:98 offset1:114
	v_bfe_u32 v0, v59, 16, 1
	s_ashr_i32 s7, s6, 31
	v_add3_u32 v0, v59, v0, s66
	v_bfe_u32 v1, v103, 16, 1
	s_lshl_b64 s[6:7], s[6:7], 1
	v_lshrrev_b32_e32 v0, 16, v0
	v_add3_u32 v1, v103, v1, s66
	s_add_u32 s6, s19, s6
	v_and_or_b32 v0, v1, s63, v0
	s_addc_u32 s7, s24, s7
	v_mov_b32_e32 v65, v197
	ds_write2_b32 v98, v3, v0 offset0:227 offset1:243
	v_lshl_add_u64 v[0:1], s[6:7], 0, v[64:65]
	s_sub_i32 s6, s8, s9
	s_add_i32 s6, s6, s82
	s_waitcnt lgkmcnt(0)
	s_barrier
	v_lshl_add_u64 v[8:9], v[0:1], 0, s[50:51]
	ds_read2_b32 v[0:1], v82 offset1:1
	ds_read2_b32 v[2:3], v82 offset0:2 offset1:3
	v_add_u32_e32 v12, s6, v83
	v_add_u32_e32 v4, 0xfffa8000, v12
	v_mad_i64_i32 v[10:11], s[6:7], v4, s88, v[8:9]
	ds_read2_b32 v[4:5], v96 offset1:1
	ds_read2_b32 v[6:7], v97 offset1:1
	s_waitcnt lgkmcnt(2)
	global_store_dwordx4 v[10:11], v[0:3], off nt
	s_nop 1
	v_add_u32_e32 v0, 0xfffa8010, v12
	v_mad_i64_i32 v[0:1], s[6:7], v0, s88, v[8:9]
	s_waitcnt lgkmcnt(0)
	global_store_dwordx4 v[0:1], v[4:7], off nt
	ds_read2_b32 v[0:1], v94 offset1:1
	ds_read2_b32 v[2:3], v95 offset1:1
	v_add_u32_e32 v4, 0xfffa8020, v12
	v_mad_i64_i32 v[10:11], s[6:7], v4, s88, v[8:9]
	ds_read2_b32 v[4:5], v92 offset1:1
	ds_read2_b32 v[6:7], v93 offset1:1
	s_waitcnt lgkmcnt(2)
	global_store_dwordx4 v[10:11], v[0:3], off nt
	s_nop 1
	v_add_u32_e32 v0, 0xfffa8030, v12
	v_mad_i64_i32 v[0:1], s[6:7], v0, s88, v[8:9]
	s_waitcnt lgkmcnt(0)
	global_store_dwordx4 v[0:1], v[4:7], off nt
	ds_read2_b32 v[0:1], v90 offset1:1
	ds_read2_b32 v[2:3], v91 offset1:1
	v_add_u32_e32 v4, 0xfffa8040, v12
	v_mad_i64_i32 v[10:11], s[6:7], v4, s88, v[8:9]
	ds_read2_b32 v[4:5], v88 offset1:1
	ds_read2_b32 v[6:7], v89 offset1:1
	s_waitcnt lgkmcnt(2)
	global_store_dwordx4 v[10:11], v[0:3], off nt
	s_nop 1
	v_add_u32_e32 v0, 0xfffa8050, v12
	v_mad_i64_i32 v[0:1], s[6:7], v0, s88, v[8:9]
	s_waitcnt lgkmcnt(0)
	global_store_dwordx4 v[0:1], v[4:7], off nt
	ds_read2_b32 v[0:1], v86 offset1:1
	ds_read2_b32 v[2:3], v87 offset1:1
	v_add_u32_e32 v4, 0xfffa8060, v12
	v_mad_i64_i32 v[10:11], s[6:7], v4, s88, v[8:9]
	ds_read2_b32 v[4:5], v84 offset1:1
	ds_read2_b32 v[6:7], v85 offset1:1
	s_waitcnt lgkmcnt(2)
	global_store_dwordx4 v[10:11], v[0:3], off nt
	s_nop 1
	v_add_u32_e32 v0, 0xfffa8070, v12
	v_mad_i64_i32 v[0:1], s[6:7], v0, s88, v[8:9]
	s_waitcnt lgkmcnt(0)
	global_store_dwordx4 v[0:1], v[4:7], off nt
	s_barrier
	s_mov_b64 s[6:7], 0
